# sample gather loop rewritten by hand: 8 rolling key slots, 32 row loads in flight per wave, no register copies
# baseline (speedup 1.0000x reference)
.LBB0_1521:
	v_cmp_ge_f32_e32 vcc, v201, v0
	v_cmp_ge_f32_e64 s[50:51], v209, v0
	s_nop 0
	v_cndmask_b32_e64 v7, 0, 1, vcc
	v_cmp_ge_f32_e32 vcc, v200, v0
	s_nop 1
	v_addc_co_u32_e32 v7, vcc, 0, v7, vcc
	v_cmp_ge_f32_e32 vcc, v202, v0
	s_nop 1
	v_cndmask_b32_e64 v8, 0, 1, vcc
	v_cmp_ge_f32_e32 vcc, v112, v0
	s_nop 1
	v_addc_co_u32_e32 v7, vcc, v7, v8, vcc
	v_cmp_ge_f32_e32 vcc, v113, v0
	s_nop 1
	v_cndmask_b32_e64 v8, 0, 1, vcc
	v_cmp_ge_f32_e32 vcc, v114, v0
	s_nop 1
	v_addc_co_u32_e32 v7, vcc, v7, v8, vcc
	v_cmp_ge_f32_e32 vcc, v115, v0
	s_nop 1
	v_cndmask_b32_e64 v8, 0, 1, vcc
	v_cmp_ge_f32_e32 vcc, v116, v0
	s_nop 1
	v_addc_co_u32_e32 v7, vcc, v7, v8, vcc
	v_cmp_ge_f32_e32 vcc, v117, v0
	s_nop 1
	v_cndmask_b32_e64 v8, 0, 1, vcc
	v_cmp_ge_f32_e32 vcc, v118, v0
	s_nop 1
	v_addc_co_u32_e32 v7, vcc, v7, v8, vcc
	v_cmp_ge_f32_e32 vcc, v119, v0
	s_nop 1
	v_cndmask_b32_e64 v8, 0, 1, vcc
	v_cmp_ge_f32_e32 vcc, v205, v0
	s_nop 1
	v_addc_co_u32_e32 v7, vcc, v7, v8, vcc
	v_cmp_ge_f32_e32 vcc, v206, v0
	s_nop 1
	v_cndmask_b32_e64 v8, 0, 1, vcc
	v_cmp_ge_f32_e32 vcc, v207, v0
	s_nop 1
	v_addc_co_u32_e32 v7, vcc, v7, v8, vcc
	v_cmp_ge_f32_e32 vcc, v208, v0
	s_nop 1
	v_cndmask_b32_e64 v8, 0, 1, vcc
	s_andn2_b64 vcc, exec, s[60:61]
	v_addc_co_u32_e64 v7, s[50:51], v7, v8, s[50:51]
	s_cbranch_vccnz .LBB0_1527
	v_cmp_ge_f32_e32 vcc, v210, v0
	s_nop 1
	v_cndmask_b32_e64 v8, 0, 1, vcc
	v_cmp_ge_f32_e32 vcc, v212, v0
	s_nop 1
	v_cndmask_b32_e64 v9, 0, 1, vcc
	v_cmp_ge_f32_e32 vcc, v214, v0
	s_nop 1
	v_cndmask_b32_e64 v10, 0, 1, vcc
	v_cmp_ge_f32_e32 vcc, v217, v0
	s_nop 1
	v_cndmask_b32_e64 v11, 0, 1, vcc
	v_cmp_ge_f32_e32 vcc, v211, v0
	s_nop 1
	v_addc_co_u32_e32 v8, vcc, 0, v8, vcc
	v_cmp_ge_f32_e32 vcc, v213, v0
	s_nop 1
	v_addc_co_u32_e32 v8, vcc, v8, v9, vcc
	v_cmp_ge_f32_e32 vcc, v216, v0
	s_nop 1
	v_addc_co_u32_e32 v8, vcc, v8, v10, vcc
	v_cmp_ge_f32_e32 vcc, v218, v0
	s_nop 1
	v_addc_co_u32_e32 v8, vcc, v8, v11, vcc
	v_add_u32_e32 v7, v8, v7
	s_andn2_b64 vcc, exec, s[62:63]
	s_cbranch_vccz .LBB0_1528

.LBB0_1524:
	v_cmp_ge_f32_e32 vcc, v227, v0
	s_nop 1
	v_cndmask_b32_e64 v8, 0, 1, vcc
	v_cmp_ge_f32_e32 vcc, v229, v0
	s_nop 1
	v_cndmask_b32_e64 v9, 0, 1, vcc
	v_cmp_ge_f32_e32 vcc, v231, v0
	s_nop 1
	v_cndmask_b32_e64 v10, 0, 1, vcc
	v_cmp_ge_f32_e32 vcc, v233, v0
	s_nop 1
	v_cndmask_b32_e64 v11, 0, 1, vcc
	v_cmp_ge_f32_e32 vcc, v228, v0
	s_nop 1
	v_addc_co_u32_e32 v8, vcc, 0, v8, vcc
	v_cmp_ge_f32_e32 vcc, v230, v0
	s_nop 1
	v_addc_co_u32_e32 v8, vcc, v8, v9, vcc
	v_cmp_ge_f32_e32 vcc, v232, v0
	s_nop 1
	v_addc_co_u32_e32 v8, vcc, v8, v10, vcc
	v_cmp_ge_f32_e32 vcc, v234, v0
	s_nop 1
	v_addc_co_u32_e32 v8, vcc, v8, v11, vcc
	v_add_u32_e32 v7, v8, v7
	s_andn2_b64 vcc, exec, s[66:67]
	s_cbranch_vccz .LBB0_1530

.LBB0_1526:
	v_cmp_ge_f32_e32 vcc, v243, v0
	s_nop 1
	v_cndmask_b32_e64 v8, 0, 1, vcc
	v_cmp_ge_f32_e32 vcc, v245, v0
	s_nop 1
	v_cndmask_b32_e64 v9, 0, 1, vcc
	v_cmp_ge_f32_e32 vcc, v247, v0
	s_nop 1
	v_cndmask_b32_e64 v10, 0, 1, vcc
	v_cmp_ge_f32_e32 vcc, v249, v0
	s_nop 1
	v_cndmask_b32_e64 v11, 0, 1, vcc
	v_cmp_ge_f32_e32 vcc, v244, v0
	s_nop 1
	v_addc_co_u32_e32 v8, vcc, 0, v8, vcc
	v_cmp_ge_f32_e32 vcc, v246, v0
	s_nop 1
	v_addc_co_u32_e32 v8, vcc, v8, v9, vcc
	v_cmp_ge_f32_e32 vcc, v248, v0
	s_nop 1
	v_addc_co_u32_e32 v8, vcc, v8, v10, vcc
	v_cmp_ge_f32_e32 vcc, v250, v0
	s_nop 1
	v_addc_co_u32_e32 v8, vcc, v8, v11, vcc
	v_add_u32_e32 v7, v8, v7
	s_andn2_b64 vcc, exec, s[70:71]
	s_cbranch_vccz .LBB0_1532
	s_branch .LBB0_1533

.LBB0_1528:
	v_cmp_ge_f32_e32 vcc, v219, v0
	s_nop 1
	v_cndmask_b32_e64 v8, 0, 1, vcc
	v_cmp_ge_f32_e32 vcc, v221, v0
	s_nop 1
	v_cndmask_b32_e64 v9, 0, 1, vcc
	v_cmp_ge_f32_e32 vcc, v223, v0
	s_nop 1
	v_cndmask_b32_e64 v10, 0, 1, vcc
	v_cmp_ge_f32_e32 vcc, v225, v0
	s_nop 1
	v_cndmask_b32_e64 v11, 0, 1, vcc
	v_cmp_ge_f32_e32 vcc, v220, v0
	s_nop 1
	v_addc_co_u32_e32 v8, vcc, 0, v8, vcc
	v_cmp_ge_f32_e32 vcc, v222, v0
	s_nop 1
	v_addc_co_u32_e32 v8, vcc, v8, v9, vcc
	v_cmp_ge_f32_e32 vcc, v224, v0
	s_nop 1
	v_addc_co_u32_e32 v8, vcc, v8, v10, vcc
	v_cmp_ge_f32_e32 vcc, v226, v0
	s_nop 1
	v_addc_co_u32_e32 v8, vcc, v8, v11, vcc
	v_add_u32_e32 v7, v8, v7
	s_andn2_b64 vcc, exec, s[64:65]
	s_cbranch_vccz .LBB0_1524

.LBB0_1530:
	v_cmp_ge_f32_e32 vcc, v235, v0
	s_nop 1
	v_cndmask_b32_e64 v8, 0, 1, vcc
	v_cmp_ge_f32_e32 vcc, v237, v0
	s_nop 1
	v_cndmask_b32_e64 v9, 0, 1, vcc
	v_cmp_ge_f32_e32 vcc, v239, v0
	s_nop 1
	v_cndmask_b32_e64 v10, 0, 1, vcc
	v_cmp_ge_f32_e32 vcc, v241, v0
	s_nop 1
	v_cndmask_b32_e64 v11, 0, 1, vcc
	v_cmp_ge_f32_e32 vcc, v236, v0
	s_nop 1
	v_addc_co_u32_e32 v8, vcc, 0, v8, vcc
	v_cmp_ge_f32_e32 vcc, v238, v0
	s_nop 1
	v_addc_co_u32_e32 v8, vcc, v8, v9, vcc
	v_cmp_ge_f32_e32 vcc, v240, v0
	s_nop 1
	v_addc_co_u32_e32 v8, vcc, v8, v10, vcc
	v_cmp_ge_f32_e32 vcc, v242, v0
	s_nop 1
	v_addc_co_u32_e32 v8, vcc, v8, v11, vcc
	v_add_u32_e32 v7, v8, v7
	s_andn2_b64 vcc, exec, s[68:69]
	s_cbranch_vccz .LBB0_1526

.LBB0_1532:
	v_cmp_ge_f32_e32 vcc, v251, v0
	s_nop 1
	v_cndmask_b32_e64 v8, 0, 1, vcc
	v_cmp_ge_f32_e32 vcc, v253, v0
	s_nop 1
	v_cndmask_b32_e64 v9, 0, 1, vcc
	v_cmp_ge_f32_e32 vcc, v133, v0
	s_nop 1
	v_cndmask_b32_e64 v10, 0, 1, vcc
	v_cmp_ge_f32_e32 vcc, v80, v0
	s_nop 1
	v_cndmask_b32_e64 v11, 0, 1, vcc
	v_cmp_ge_f32_e32 vcc, v252, v0
	s_nop 1
	v_addc_co_u32_e32 v8, vcc, 0, v8, vcc
	v_cmp_ge_f32_e32 vcc, v215, v0
	s_nop 1
	v_addc_co_u32_e32 v8, vcc, v8, v9, vcc
	v_cmp_ge_f32_e32 vcc, v84, v0
	s_nop 1
	v_addc_co_u32_e32 v8, vcc, v8, v10, vcc
	v_cmp_ge_f32_e32 vcc, v16, v0
	s_nop 1
	v_addc_co_u32_e32 v8, vcc, v8, v11, vcc
	v_add_u32_e32 v7, v8, v7

.LBB0_2124:
	v_cmp_ge_f32_e32 vcc, v201, v0
	v_cmp_ge_f32_e64 s[52:53], v209, v0
	s_nop 0
	v_cndmask_b32_e64 v7, 0, 1, vcc
	v_cmp_ge_f32_e32 vcc, v200, v0
	s_nop 1
	v_addc_co_u32_e32 v7, vcc, 0, v7, vcc
	v_cmp_ge_f32_e32 vcc, v202, v0
	s_nop 1
	v_cndmask_b32_e64 v8, 0, 1, vcc
	v_cmp_ge_f32_e32 vcc, v112, v0
	s_nop 1
	v_addc_co_u32_e32 v7, vcc, v7, v8, vcc
	v_cmp_ge_f32_e32 vcc, v113, v0
	s_nop 1
	v_cndmask_b32_e64 v8, 0, 1, vcc
	v_cmp_ge_f32_e32 vcc, v114, v0
	s_nop 1
	v_addc_co_u32_e32 v7, vcc, v7, v8, vcc
	v_cmp_ge_f32_e32 vcc, v115, v0
	s_nop 1
	v_cndmask_b32_e64 v8, 0, 1, vcc
	v_cmp_ge_f32_e32 vcc, v116, v0
	s_nop 1
	v_addc_co_u32_e32 v7, vcc, v7, v8, vcc
	v_cmp_ge_f32_e32 vcc, v117, v0
	s_nop 1
	v_cndmask_b32_e64 v8, 0, 1, vcc
	v_cmp_ge_f32_e32 vcc, v118, v0
	s_nop 1
	v_addc_co_u32_e32 v7, vcc, v7, v8, vcc
	v_cmp_ge_f32_e32 vcc, v119, v0
	s_nop 1
	v_cndmask_b32_e64 v8, 0, 1, vcc
	v_cmp_ge_f32_e32 vcc, v205, v0
	s_nop 1
	v_addc_co_u32_e32 v7, vcc, v7, v8, vcc
	v_cmp_ge_f32_e32 vcc, v206, v0
	s_nop 1
	v_cndmask_b32_e64 v8, 0, 1, vcc
	v_cmp_ge_f32_e32 vcc, v207, v0
	s_nop 1
	v_addc_co_u32_e32 v7, vcc, v7, v8, vcc
	v_cmp_ge_f32_e32 vcc, v208, v0
	s_nop 1
	v_cndmask_b32_e64 v8, 0, 1, vcc
	s_andn2_b64 vcc, exec, s[62:63]
	v_addc_co_u32_e64 v7, s[52:53], v7, v8, s[52:53]
	s_cbranch_vccnz .LBB0_2130
	v_cmp_ge_f32_e32 vcc, v210, v0
	s_nop 1
	v_cndmask_b32_e64 v8, 0, 1, vcc
	v_cmp_ge_f32_e32 vcc, v212, v0
	s_nop 1
	v_cndmask_b32_e64 v9, 0, 1, vcc
	v_cmp_ge_f32_e32 vcc, v214, v0
	s_nop 1
	v_cndmask_b32_e64 v10, 0, 1, vcc
	v_cmp_ge_f32_e32 vcc, v217, v0
	s_nop 1
	v_cndmask_b32_e64 v11, 0, 1, vcc
	v_cmp_ge_f32_e32 vcc, v211, v0
	s_nop 1
	v_addc_co_u32_e32 v8, vcc, 0, v8, vcc
	v_cmp_ge_f32_e32 vcc, v213, v0
	s_nop 1
	v_addc_co_u32_e32 v8, vcc, v8, v9, vcc
	v_cmp_ge_f32_e32 vcc, v216, v0
	s_nop 1
	v_addc_co_u32_e32 v8, vcc, v8, v10, vcc
	v_cmp_ge_f32_e32 vcc, v218, v0
	s_nop 1
	v_addc_co_u32_e32 v8, vcc, v8, v11, vcc
	v_add_u32_e32 v7, v8, v7
	s_andn2_b64 vcc, exec, s[64:65]
	s_cbranch_vccz .LBB0_2131

.LBB0_2127:
	v_cmp_ge_f32_e32 vcc, v227, v0
	s_nop 1
	v_cndmask_b32_e64 v8, 0, 1, vcc
	v_cmp_ge_f32_e32 vcc, v229, v0
	s_nop 1
	v_cndmask_b32_e64 v9, 0, 1, vcc
	v_cmp_ge_f32_e32 vcc, v231, v0
	s_nop 1
	v_cndmask_b32_e64 v10, 0, 1, vcc
	v_cmp_ge_f32_e32 vcc, v233, v0
	s_nop 1
	v_cndmask_b32_e64 v11, 0, 1, vcc
	v_cmp_ge_f32_e32 vcc, v228, v0
	s_nop 1
	v_addc_co_u32_e32 v8, vcc, 0, v8, vcc
	v_cmp_ge_f32_e32 vcc, v230, v0
	s_nop 1
	v_addc_co_u32_e32 v8, vcc, v8, v9, vcc
	v_cmp_ge_f32_e32 vcc, v232, v0
	s_nop 1
	v_addc_co_u32_e32 v8, vcc, v8, v10, vcc
	v_cmp_ge_f32_e32 vcc, v234, v0
	s_nop 1
	v_addc_co_u32_e32 v8, vcc, v8, v11, vcc
	v_add_u32_e32 v7, v8, v7
	s_andn2_b64 vcc, exec, s[68:69]
	s_cbranch_vccz .LBB0_2133

.LBB0_2129:
	v_cmp_ge_f32_e32 vcc, v243, v0
	s_nop 1
	v_cndmask_b32_e64 v8, 0, 1, vcc
	v_cmp_ge_f32_e32 vcc, v245, v0
	s_nop 1
	v_cndmask_b32_e64 v9, 0, 1, vcc
	v_cmp_ge_f32_e32 vcc, v247, v0
	s_nop 1
	v_cndmask_b32_e64 v10, 0, 1, vcc
	v_cmp_ge_f32_e32 vcc, v249, v0
	s_nop 1
	v_cndmask_b32_e64 v11, 0, 1, vcc
	v_cmp_ge_f32_e32 vcc, v244, v0
	s_nop 1
	v_addc_co_u32_e32 v8, vcc, 0, v8, vcc
	v_cmp_ge_f32_e32 vcc, v246, v0
	s_nop 1
	v_addc_co_u32_e32 v8, vcc, v8, v9, vcc
	v_cmp_ge_f32_e32 vcc, v248, v0
	s_nop 1
	v_addc_co_u32_e32 v8, vcc, v8, v10, vcc
	v_cmp_ge_f32_e32 vcc, v250, v0
	s_nop 1
	v_addc_co_u32_e32 v8, vcc, v8, v11, vcc
	v_add_u32_e32 v7, v8, v7
	s_andn2_b64 vcc, exec, s[72:73]
	s_cbranch_vccz .LBB0_2135
	s_branch .LBB0_2136

.LBB0_2131:
	v_cmp_ge_f32_e32 vcc, v219, v0
	s_nop 1
	v_cndmask_b32_e64 v8, 0, 1, vcc
	v_cmp_ge_f32_e32 vcc, v221, v0
	s_nop 1
	v_cndmask_b32_e64 v9, 0, 1, vcc
	v_cmp_ge_f32_e32 vcc, v223, v0
	s_nop 1
	v_cndmask_b32_e64 v10, 0, 1, vcc
	v_cmp_ge_f32_e32 vcc, v225, v0
	s_nop 1
	v_cndmask_b32_e64 v11, 0, 1, vcc
	v_cmp_ge_f32_e32 vcc, v220, v0
	s_nop 1
	v_addc_co_u32_e32 v8, vcc, 0, v8, vcc
	v_cmp_ge_f32_e32 vcc, v222, v0
	s_nop 1
	v_addc_co_u32_e32 v8, vcc, v8, v9, vcc
	v_cmp_ge_f32_e32 vcc, v224, v0
	s_nop 1
	v_addc_co_u32_e32 v8, vcc, v8, v10, vcc
	v_cmp_ge_f32_e32 vcc, v226, v0
	s_nop 1
	v_addc_co_u32_e32 v8, vcc, v8, v11, vcc
	v_add_u32_e32 v7, v8, v7
	s_andn2_b64 vcc, exec, s[66:67]
	s_cbranch_vccz .LBB0_2127

.LBB0_2133:
	v_cmp_ge_f32_e32 vcc, v235, v0
	s_nop 1
	v_cndmask_b32_e64 v8, 0, 1, vcc
	v_cmp_ge_f32_e32 vcc, v237, v0
	s_nop 1
	v_cndmask_b32_e64 v9, 0, 1, vcc
	v_cmp_ge_f32_e32 vcc, v239, v0
	s_nop 1
	v_cndmask_b32_e64 v10, 0, 1, vcc
	v_cmp_ge_f32_e32 vcc, v241, v0
	s_nop 1
	v_cndmask_b32_e64 v11, 0, 1, vcc
	v_cmp_ge_f32_e32 vcc, v236, v0
	s_nop 1
	v_addc_co_u32_e32 v8, vcc, 0, v8, vcc
	v_cmp_ge_f32_e32 vcc, v238, v0
	s_nop 1
	v_addc_co_u32_e32 v8, vcc, v8, v9, vcc
	v_cmp_ge_f32_e32 vcc, v240, v0
	s_nop 1
	v_addc_co_u32_e32 v8, vcc, v8, v10, vcc
	v_cmp_ge_f32_e32 vcc, v242, v0
	s_nop 1
	v_addc_co_u32_e32 v8, vcc, v8, v11, vcc
	v_add_u32_e32 v7, v8, v7
	s_andn2_b64 vcc, exec, s[70:71]
	s_cbranch_vccz .LBB0_2129

.LBB0_2447:
	s_or_b64 exec, exec, s[20:21]
	s_mov_b32 s23, s31
	v_lshl_add_u64 v[0:1], v[150:151], 0, s[22:23]
	global_load_dwordx4 v[4:7], v[0:1], off
	s_lshl_b32 s20, s55, 8
	s_add_i32 s20, s20, 0
	v_mov_b32_e32 v0, s20
	s_waitcnt lgkmcnt(0)
	s_barrier
	v_lshlrev_b32_e32 v220, 2, v148
	v_mov_b32_e32 v139, v138
	v_mbcnt_lo_u32_b32 v236, -1, 0
	v_mbcnt_hi_u32_b32 v236, -1, v236
	v_and_b32_e32 v236, 31, v236
	v_lshl_add_u32 v236, v236, 3, s20
	ds_read_b64 v[222:223], v236 offset:28672
	ds_read_b64 v[224:225], v236 offset:30720
	s_lshl_b32 s23, s58, 9
	v_mov_b32_e32 v226, s24
	v_mov_b32_e32 v227, s25
	s_waitcnt vmcnt(0)
	v_lshlrev_b32_e32 v156, 16, v4
	v_and_b32_e32 v157, 0xffff0000, v5
	v_and_b32_e32 v158, 0xffff0000, v4
	v_lshlrev_b32_e32 v159, 16, v5
	v_lshlrev_b32_e32 v161, 16, v7
	v_lshlrev_b32_e32 v160, 16, v6
	v_and_b32_e32 v163, 0xffff0000, v7
	v_and_b32_e32 v162, 0xffff0000, v6
	v_mov_b32_e32 v177, 0xff800000
	v_mov_b32_e32 v176, 0
	v_mov_b32_e32 v228, 0
	v_mov_b32_e32 v229, 0
	v_mov_b32_e32 v230, 0
	v_mov_b32_e32 v231, 0
	v_mov_b32_e32 v232, 0
	v_mov_b32_e32 v233, 0
	v_mov_b32_e32 v234, 0
	v_mov_b32_e32 v235, 0
	v_mov_b32_e32 v171, 0
	v_mov_b32_e32 v173, 0
	s_waitcnt lgkmcnt(0)
	v_cmp_ne_u64_e32 vcc, 0, v[222:223]
	s_nop 1
	s_mov_b32 s98, vcc_lo
	v_cndmask_b32_e32 v222, v226, v222, vcc
	v_cndmask_b32_e32 v223, v227, v223, vcc
	v_cndmask_b32_e32 v224, v226, v224, vcc
	v_cndmask_b32_e32 v225, v227, v225, vcc
	s_nop 0
	v_readlane_b32 s38, v222, 0
	v_readlane_b32 s39, v223, 0
	v_readlane_b32 s40, v224, 0
	v_readlane_b32 s41, v225, 0
	v_readlane_b32 s42, v222, 1
	v_readlane_b32 s43, v223, 1
	v_readlane_b32 s100, v224, 1
	v_readlane_b32 s101, v225, 1
	global_load_dwordx4 v[4:7], v220, s[38:39] offset:16
	global_load_dwordx4 v[0:3], v220, s[38:39]
	global_load_dwordx4 v[12:15], v220, s[40:41] offset:16
	global_load_dwordx4 v[8:11], v220, s[40:41]
	v_readlane_b32 s38, v222, 2
	v_readlane_b32 s39, v223, 2
	v_readlane_b32 s40, v224, 2
	v_readlane_b32 s41, v225, 2
	global_load_dwordx4 v[20:23], v220, s[42:43] offset:16
	global_load_dwordx4 v[16:19], v220, s[42:43]
	global_load_dwordx4 v[28:31], v220, s[100:101] offset:16
	global_load_dwordx4 v[24:27], v220, s[100:101]
	v_readlane_b32 s42, v222, 3
	v_readlane_b32 s43, v223, 3
	v_readlane_b32 s100, v224, 3
	v_readlane_b32 s101, v225, 3
	global_load_dwordx4 v[36:39], v220, s[38:39] offset:16
	global_load_dwordx4 v[32:35], v220, s[38:39]
	global_load_dwordx4 v[44:47], v220, s[40:41] offset:16
	global_load_dwordx4 v[40:43], v220, s[40:41]
	v_readlane_b32 s38, v222, 4
	v_readlane_b32 s39, v223, 4
	v_readlane_b32 s40, v224, 4
	v_readlane_b32 s41, v225, 4
	global_load_dwordx4 v[52:55], v220, s[42:43] offset:16
	global_load_dwordx4 v[48:51], v220, s[42:43]
	global_load_dwordx4 v[60:63], v220, s[100:101] offset:16
	global_load_dwordx4 v[56:59], v220, s[100:101]
	v_readlane_b32 s42, v222, 5
	v_readlane_b32 s43, v223, 5
	v_readlane_b32 s100, v224, 5
	v_readlane_b32 s101, v225, 5
	global_load_dwordx4 v[68:71], v220, s[38:39] offset:16
	global_load_dwordx4 v[64:67], v220, s[38:39]
	global_load_dwordx4 v[76:79], v220, s[40:41] offset:16
	global_load_dwordx4 v[72:75], v220, s[40:41]
	v_readlane_b32 s38, v222, 6
	v_readlane_b32 s39, v223, 6
	v_readlane_b32 s40, v224, 6
	v_readlane_b32 s41, v225, 6
	global_load_dwordx4 v[84:87], v220, s[42:43] offset:16
	global_load_dwordx4 v[80:83], v220, s[42:43]
	global_load_dwordx4 v[92:95], v220, s[100:101] offset:16
	global_load_dwordx4 v[88:91], v220, s[100:101]
	v_readlane_b32 s42, v222, 7
	v_readlane_b32 s43, v223, 7
	v_readlane_b32 s100, v224, 7
	v_readlane_b32 s101, v225, 7
	global_load_dwordx4 v[100:103], v220, s[38:39] offset:16
	global_load_dwordx4 v[96:99], v220, s[38:39]
	global_load_dwordx4 v[108:111], v220, s[40:41] offset:16
	global_load_dwordx4 v[104:107], v220, s[40:41]
	s_nop 4
	global_load_dwordx4 v[116:119], v220, s[42:43] offset:16
	global_load_dwordx4 v[112:115], v220, s[42:43]
	global_load_dwordx4 v[124:127], v220, s[100:101] offset:16
	global_load_dwordx4 v[120:123], v220, s[100:101]
	s_mov_b32 s99, 8
.Lgx0_loop:
	s_waitcnt vmcnt(28)
	s_mov_b32 s21, s99
	v_readlane_b32 s38, v222, s21
	v_readlane_b32 s39, v223, s21
	v_readlane_b32 s40, v224, s21
	v_readlane_b32 s41, v225, s21
	s_bitcmp1_b32 s98, 0
	s_cbranch_scc0 .Lgx0_sk0
	v_mul_f32_e32 v164, v0, v156
	v_mul_f32_e32 v165, v3, v157
	v_mul_f32_e32 v166, v5, v162
	v_mul_f32_e32 v167, v7, v163
	v_fmac_f32_e32 v164, v1, v158
	v_fmac_f32_e32 v165, v2, v159
	v_fmac_f32_e32 v166, v4, v160
	v_fmac_f32_e32 v167, v6, v161
	v_add_f32_e32 v164, v164, v165
	v_add_f32_e32 v164, v164, v166
	v_add_f32_e32 v164, v167, v164
	v_max_f32_e32 v168, v177, v177
	s_nop 0
	v_add_f32_dpp v164, v164, v164 quad_perm:[1,0,3,2] row_mask:0xf bank_mask:0xf bound_ctrl:1
	s_nop 1
	v_add_f32_dpp v164, v164, v164 quad_perm:[2,3,0,1] row_mask:0xf bank_mask:0xf bound_ctrl:1
	s_nop 1
	v_add_f32_dpp v164, v164, v164 row_half_mirror row_mask:0xf bank_mask:0xf bound_ctrl:1
	v_max_f32_e32 v168, v168, v164
	v_sub_f32_e32 v164, v164, v168
	v_sub_f32_e32 v172, v177, v168
	v_exp_f32_e32 v170, v164
	v_exp_f32_e32 v172, v172
	v_mov_b32_e32 v177, v168
	v_pk_mul_f32 v[174:175], v[8:9], v[170:171] op_sel_hi:[1,0]
	v_pk_mul_f32 v[178:179], v[12:13], v[170:171] op_sel_hi:[1,0]
	v_fma_f32 v176, v176, v172, v170
	v_pk_fma_f32 v[228:229], v[228:229], v[172:173], v[174:175] op_sel_hi:[1,0,1]
	v_pk_mul_f32 v[174:175], v[10:11], v[170:171] op_sel_hi:[1,0]
	v_pk_fma_f32 v[232:233], v[232:233], v[172:173], v[178:179] op_sel_hi:[1,0,1]
	v_pk_mul_f32 v[178:179], v[14:15], v[170:171] op_sel_hi:[1,0]
	v_pk_fma_f32 v[230:231], v[230:231], v[172:173], v[174:175] op_sel_hi:[1,0,1]
	v_pk_fma_f32 v[234:235], v[234:235], v[172:173], v[178:179] op_sel_hi:[1,0,1]
.Lgx0_sk0:
	s_lshr_b32 s98, s98, 1
	s_nop 1
	global_load_dwordx4 v[4:7], v220, s[38:39] offset:16
	global_load_dwordx4 v[0:3], v220, s[38:39]
	global_load_dwordx4 v[12:15], v220, s[40:41] offset:16
	global_load_dwordx4 v[8:11], v220, s[40:41]
	s_waitcnt vmcnt(28)
	s_add_i32 s21, s99, 1
	v_readlane_b32 s42, v222, s21
	v_readlane_b32 s43, v223, s21
	v_readlane_b32 s100, v224, s21
	v_readlane_b32 s101, v225, s21
	s_bitcmp1_b32 s98, 0
	s_cbranch_scc0 .Lgx0_sk1
	v_mul_f32_e32 v164, v16, v156
	v_mul_f32_e32 v165, v19, v157
	v_mul_f32_e32 v166, v21, v162
	v_mul_f32_e32 v167, v23, v163
	v_fmac_f32_e32 v164, v17, v158
	v_fmac_f32_e32 v165, v18, v159
	v_fmac_f32_e32 v166, v20, v160
	v_fmac_f32_e32 v167, v22, v161
	v_add_f32_e32 v164, v164, v165
	v_add_f32_e32 v164, v164, v166
	v_add_f32_e32 v164, v167, v164
	v_max_f32_e32 v168, v177, v177
	s_nop 0
	v_add_f32_dpp v164, v164, v164 quad_perm:[1,0,3,2] row_mask:0xf bank_mask:0xf bound_ctrl:1
	s_nop 1
	v_add_f32_dpp v164, v164, v164 quad_perm:[2,3,0,1] row_mask:0xf bank_mask:0xf bound_ctrl:1
	s_nop 1
	v_add_f32_dpp v164, v164, v164 row_half_mirror row_mask:0xf bank_mask:0xf bound_ctrl:1
	v_max_f32_e32 v168, v168, v164
	v_sub_f32_e32 v164, v164, v168
	v_sub_f32_e32 v172, v177, v168
	v_exp_f32_e32 v170, v164
	v_exp_f32_e32 v172, v172
	v_mov_b32_e32 v177, v168
	v_pk_mul_f32 v[174:175], v[24:25], v[170:171] op_sel_hi:[1,0]
	v_pk_mul_f32 v[178:179], v[28:29], v[170:171] op_sel_hi:[1,0]
	v_fma_f32 v176, v176, v172, v170
	v_pk_fma_f32 v[228:229], v[228:229], v[172:173], v[174:175] op_sel_hi:[1,0,1]
	v_pk_mul_f32 v[174:175], v[26:27], v[170:171] op_sel_hi:[1,0]
	v_pk_fma_f32 v[232:233], v[232:233], v[172:173], v[178:179] op_sel_hi:[1,0,1]
	v_pk_mul_f32 v[178:179], v[30:31], v[170:171] op_sel_hi:[1,0]
	v_pk_fma_f32 v[230:231], v[230:231], v[172:173], v[174:175] op_sel_hi:[1,0,1]
	v_pk_fma_f32 v[234:235], v[234:235], v[172:173], v[178:179] op_sel_hi:[1,0,1]
.Lgx0_sk1:
	s_lshr_b32 s98, s98, 1
	s_nop 1
	global_load_dwordx4 v[20:23], v220, s[42:43] offset:16
	global_load_dwordx4 v[16:19], v220, s[42:43]
	global_load_dwordx4 v[28:31], v220, s[100:101] offset:16
	global_load_dwordx4 v[24:27], v220, s[100:101]
	s_waitcnt vmcnt(28)
	s_add_i32 s21, s99, 2
	v_readlane_b32 s38, v222, s21
	v_readlane_b32 s39, v223, s21
	v_readlane_b32 s40, v224, s21
	v_readlane_b32 s41, v225, s21
	s_bitcmp1_b32 s98, 0
	s_cbranch_scc0 .Lgx0_sk2
	v_mul_f32_e32 v164, v32, v156
	v_mul_f32_e32 v165, v35, v157
	v_mul_f32_e32 v166, v37, v162
	v_mul_f32_e32 v167, v39, v163
	v_fmac_f32_e32 v164, v33, v158
	v_fmac_f32_e32 v165, v34, v159
	v_fmac_f32_e32 v166, v36, v160
	v_fmac_f32_e32 v167, v38, v161
	v_add_f32_e32 v164, v164, v165
	v_add_f32_e32 v164, v164, v166
	v_add_f32_e32 v164, v167, v164
	v_max_f32_e32 v168, v177, v177
	s_nop 0
	v_add_f32_dpp v164, v164, v164 quad_perm:[1,0,3,2] row_mask:0xf bank_mask:0xf bound_ctrl:1
	s_nop 1
	v_add_f32_dpp v164, v164, v164 quad_perm:[2,3,0,1] row_mask:0xf bank_mask:0xf bound_ctrl:1
	s_nop 1
	v_add_f32_dpp v164, v164, v164 row_half_mirror row_mask:0xf bank_mask:0xf bound_ctrl:1
	v_max_f32_e32 v168, v168, v164
	v_sub_f32_e32 v164, v164, v168
	v_sub_f32_e32 v172, v177, v168
	v_exp_f32_e32 v170, v164
	v_exp_f32_e32 v172, v172
	v_mov_b32_e32 v177, v168
	v_pk_mul_f32 v[174:175], v[40:41], v[170:171] op_sel_hi:[1,0]
	v_pk_mul_f32 v[178:179], v[44:45], v[170:171] op_sel_hi:[1,0]
	v_fma_f32 v176, v176, v172, v170
	v_pk_fma_f32 v[228:229], v[228:229], v[172:173], v[174:175] op_sel_hi:[1,0,1]
	v_pk_mul_f32 v[174:175], v[42:43], v[170:171] op_sel_hi:[1,0]
	v_pk_fma_f32 v[232:233], v[232:233], v[172:173], v[178:179] op_sel_hi:[1,0,1]
	v_pk_mul_f32 v[178:179], v[46:47], v[170:171] op_sel_hi:[1,0]
	v_pk_fma_f32 v[230:231], v[230:231], v[172:173], v[174:175] op_sel_hi:[1,0,1]
	v_pk_fma_f32 v[234:235], v[234:235], v[172:173], v[178:179] op_sel_hi:[1,0,1]
.Lgx0_sk2:
	s_lshr_b32 s98, s98, 1
	s_nop 1
	global_load_dwordx4 v[36:39], v220, s[38:39] offset:16
	global_load_dwordx4 v[32:35], v220, s[38:39]
	global_load_dwordx4 v[44:47], v220, s[40:41] offset:16
	global_load_dwordx4 v[40:43], v220, s[40:41]
	s_waitcnt vmcnt(28)
	s_add_i32 s21, s99, 3
	v_readlane_b32 s42, v222, s21
	v_readlane_b32 s43, v223, s21
	v_readlane_b32 s100, v224, s21
	v_readlane_b32 s101, v225, s21
	s_bitcmp1_b32 s98, 0
	s_cbranch_scc0 .Lgx0_sk3
	v_mul_f32_e32 v164, v48, v156
	v_mul_f32_e32 v165, v51, v157
	v_mul_f32_e32 v166, v53, v162
	v_mul_f32_e32 v167, v55, v163
	v_fmac_f32_e32 v164, v49, v158
	v_fmac_f32_e32 v165, v50, v159
	v_fmac_f32_e32 v166, v52, v160
	v_fmac_f32_e32 v167, v54, v161
	v_add_f32_e32 v164, v164, v165
	v_add_f32_e32 v164, v164, v166
	v_add_f32_e32 v164, v167, v164
	v_max_f32_e32 v168, v177, v177
	s_nop 0
	v_add_f32_dpp v164, v164, v164 quad_perm:[1,0,3,2] row_mask:0xf bank_mask:0xf bound_ctrl:1
	s_nop 1
	v_add_f32_dpp v164, v164, v164 quad_perm:[2,3,0,1] row_mask:0xf bank_mask:0xf bound_ctrl:1
	s_nop 1
	v_add_f32_dpp v164, v164, v164 row_half_mirror row_mask:0xf bank_mask:0xf bound_ctrl:1
	v_max_f32_e32 v168, v168, v164
	v_sub_f32_e32 v164, v164, v168
	v_sub_f32_e32 v172, v177, v168
	v_exp_f32_e32 v170, v164
	v_exp_f32_e32 v172, v172
	v_mov_b32_e32 v177, v168
	v_pk_mul_f32 v[174:175], v[56:57], v[170:171] op_sel_hi:[1,0]
	v_pk_mul_f32 v[178:179], v[60:61], v[170:171] op_sel_hi:[1,0]
	v_fma_f32 v176, v176, v172, v170
	v_pk_fma_f32 v[228:229], v[228:229], v[172:173], v[174:175] op_sel_hi:[1,0,1]
	v_pk_mul_f32 v[174:175], v[58:59], v[170:171] op_sel_hi:[1,0]
	v_pk_fma_f32 v[232:233], v[232:233], v[172:173], v[178:179] op_sel_hi:[1,0,1]
	v_pk_mul_f32 v[178:179], v[62:63], v[170:171] op_sel_hi:[1,0]
	v_pk_fma_f32 v[230:231], v[230:231], v[172:173], v[174:175] op_sel_hi:[1,0,1]
	v_pk_fma_f32 v[234:235], v[234:235], v[172:173], v[178:179] op_sel_hi:[1,0,1]
.Lgx0_sk3:
	s_lshr_b32 s98, s98, 1
	s_nop 1
	global_load_dwordx4 v[52:55], v220, s[42:43] offset:16
	global_load_dwordx4 v[48:51], v220, s[42:43]
	global_load_dwordx4 v[60:63], v220, s[100:101] offset:16
	global_load_dwordx4 v[56:59], v220, s[100:101]
	s_waitcnt vmcnt(28)
	s_add_i32 s21, s99, 4
	v_readlane_b32 s38, v222, s21
	v_readlane_b32 s39, v223, s21
	v_readlane_b32 s40, v224, s21
	v_readlane_b32 s41, v225, s21
	s_bitcmp1_b32 s98, 0
	s_cbranch_scc0 .Lgx0_sk4
	v_mul_f32_e32 v164, v64, v156
	v_mul_f32_e32 v165, v67, v157
	v_mul_f32_e32 v166, v69, v162
	v_mul_f32_e32 v167, v71, v163
	v_fmac_f32_e32 v164, v65, v158
	v_fmac_f32_e32 v165, v66, v159
	v_fmac_f32_e32 v166, v68, v160
	v_fmac_f32_e32 v167, v70, v161
	v_add_f32_e32 v164, v164, v165
	v_add_f32_e32 v164, v164, v166
	v_add_f32_e32 v164, v167, v164
	v_max_f32_e32 v168, v177, v177
	s_nop 0
	v_add_f32_dpp v164, v164, v164 quad_perm:[1,0,3,2] row_mask:0xf bank_mask:0xf bound_ctrl:1
	s_nop 1
	v_add_f32_dpp v164, v164, v164 quad_perm:[2,3,0,1] row_mask:0xf bank_mask:0xf bound_ctrl:1
	s_nop 1
	v_add_f32_dpp v164, v164, v164 row_half_mirror row_mask:0xf bank_mask:0xf bound_ctrl:1
	v_max_f32_e32 v168, v168, v164
	v_sub_f32_e32 v164, v164, v168
	v_sub_f32_e32 v172, v177, v168
	v_exp_f32_e32 v170, v164
	v_exp_f32_e32 v172, v172
	v_mov_b32_e32 v177, v168
	v_pk_mul_f32 v[174:175], v[72:73], v[170:171] op_sel_hi:[1,0]
	v_pk_mul_f32 v[178:179], v[76:77], v[170:171] op_sel_hi:[1,0]
	v_fma_f32 v176, v176, v172, v170
	v_pk_fma_f32 v[228:229], v[228:229], v[172:173], v[174:175] op_sel_hi:[1,0,1]
	v_pk_mul_f32 v[174:175], v[74:75], v[170:171] op_sel_hi:[1,0]
	v_pk_fma_f32 v[232:233], v[232:233], v[172:173], v[178:179] op_sel_hi:[1,0,1]
	v_pk_mul_f32 v[178:179], v[78:79], v[170:171] op_sel_hi:[1,0]
	v_pk_fma_f32 v[230:231], v[230:231], v[172:173], v[174:175] op_sel_hi:[1,0,1]
	v_pk_fma_f32 v[234:235], v[234:235], v[172:173], v[178:179] op_sel_hi:[1,0,1]
.Lgx0_sk4:
	s_lshr_b32 s98, s98, 1
	s_nop 1
	global_load_dwordx4 v[68:71], v220, s[38:39] offset:16
	global_load_dwordx4 v[64:67], v220, s[38:39]
	global_load_dwordx4 v[76:79], v220, s[40:41] offset:16
	global_load_dwordx4 v[72:75], v220, s[40:41]
	s_waitcnt vmcnt(28)
	s_add_i32 s21, s99, 5
	v_readlane_b32 s42, v222, s21
	v_readlane_b32 s43, v223, s21
	v_readlane_b32 s100, v224, s21
	v_readlane_b32 s101, v225, s21
	s_bitcmp1_b32 s98, 0
	s_cbranch_scc0 .Lgx0_sk5
	v_mul_f32_e32 v164, v80, v156
	v_mul_f32_e32 v165, v83, v157
	v_mul_f32_e32 v166, v85, v162
	v_mul_f32_e32 v167, v87, v163
	v_fmac_f32_e32 v164, v81, v158
	v_fmac_f32_e32 v165, v82, v159
	v_fmac_f32_e32 v166, v84, v160
	v_fmac_f32_e32 v167, v86, v161
	v_add_f32_e32 v164, v164, v165
	v_add_f32_e32 v164, v164, v166
	v_add_f32_e32 v164, v167, v164
	v_max_f32_e32 v168, v177, v177
	s_nop 0
	v_add_f32_dpp v164, v164, v164 quad_perm:[1,0,3,2] row_mask:0xf bank_mask:0xf bound_ctrl:1
	s_nop 1
	v_add_f32_dpp v164, v164, v164 quad_perm:[2,3,0,1] row_mask:0xf bank_mask:0xf bound_ctrl:1
	s_nop 1
	v_add_f32_dpp v164, v164, v164 row_half_mirror row_mask:0xf bank_mask:0xf bound_ctrl:1
	v_max_f32_e32 v168, v168, v164
	v_sub_f32_e32 v164, v164, v168
	v_sub_f32_e32 v172, v177, v168
	v_exp_f32_e32 v170, v164
	v_exp_f32_e32 v172, v172
	v_mov_b32_e32 v177, v168
	v_pk_mul_f32 v[174:175], v[88:89], v[170:171] op_sel_hi:[1,0]
	v_pk_mul_f32 v[178:179], v[92:93], v[170:171] op_sel_hi:[1,0]
	v_fma_f32 v176, v176, v172, v170
	v_pk_fma_f32 v[228:229], v[228:229], v[172:173], v[174:175] op_sel_hi:[1,0,1]
	v_pk_mul_f32 v[174:175], v[90:91], v[170:171] op_sel_hi:[1,0]
	v_pk_fma_f32 v[232:233], v[232:233], v[172:173], v[178:179] op_sel_hi:[1,0,1]
	v_pk_mul_f32 v[178:179], v[94:95], v[170:171] op_sel_hi:[1,0]
	v_pk_fma_f32 v[230:231], v[230:231], v[172:173], v[174:175] op_sel_hi:[1,0,1]
	v_pk_fma_f32 v[234:235], v[234:235], v[172:173], v[178:179] op_sel_hi:[1,0,1]
.Lgx0_sk5:
	s_lshr_b32 s98, s98, 1
	s_nop 1
	global_load_dwordx4 v[84:87], v220, s[42:43] offset:16
	global_load_dwordx4 v[80:83], v220, s[42:43]
	global_load_dwordx4 v[92:95], v220, s[100:101] offset:16
	global_load_dwordx4 v[88:91], v220, s[100:101]
	s_waitcnt vmcnt(28)
	s_add_i32 s21, s99, 6
	v_readlane_b32 s38, v222, s21
	v_readlane_b32 s39, v223, s21
	v_readlane_b32 s40, v224, s21
	v_readlane_b32 s41, v225, s21
	s_bitcmp1_b32 s98, 0
	s_cbranch_scc0 .Lgx0_sk6
	v_mul_f32_e32 v164, v96, v156
	v_mul_f32_e32 v165, v99, v157
	v_mul_f32_e32 v166, v101, v162
	v_mul_f32_e32 v167, v103, v163
	v_fmac_f32_e32 v164, v97, v158
	v_fmac_f32_e32 v165, v98, v159
	v_fmac_f32_e32 v166, v100, v160
	v_fmac_f32_e32 v167, v102, v161
	v_add_f32_e32 v164, v164, v165
	v_add_f32_e32 v164, v164, v166
	v_add_f32_e32 v164, v167, v164
	v_max_f32_e32 v168, v177, v177
	s_nop 0
	v_add_f32_dpp v164, v164, v164 quad_perm:[1,0,3,2] row_mask:0xf bank_mask:0xf bound_ctrl:1
	s_nop 1
	v_add_f32_dpp v164, v164, v164 quad_perm:[2,3,0,1] row_mask:0xf bank_mask:0xf bound_ctrl:1
	s_nop 1
	v_add_f32_dpp v164, v164, v164 row_half_mirror row_mask:0xf bank_mask:0xf bound_ctrl:1
	v_max_f32_e32 v168, v168, v164
	v_sub_f32_e32 v164, v164, v168
	v_sub_f32_e32 v172, v177, v168
	v_exp_f32_e32 v170, v164
	v_exp_f32_e32 v172, v172
	v_mov_b32_e32 v177, v168
	v_pk_mul_f32 v[174:175], v[104:105], v[170:171] op_sel_hi:[1,0]
	v_pk_mul_f32 v[178:179], v[108:109], v[170:171] op_sel_hi:[1,0]
	v_fma_f32 v176, v176, v172, v170
	v_pk_fma_f32 v[228:229], v[228:229], v[172:173], v[174:175] op_sel_hi:[1,0,1]
	v_pk_mul_f32 v[174:175], v[106:107], v[170:171] op_sel_hi:[1,0]
	v_pk_fma_f32 v[232:233], v[232:233], v[172:173], v[178:179] op_sel_hi:[1,0,1]
	v_pk_mul_f32 v[178:179], v[110:111], v[170:171] op_sel_hi:[1,0]
	v_pk_fma_f32 v[230:231], v[230:231], v[172:173], v[174:175] op_sel_hi:[1,0,1]
	v_pk_fma_f32 v[234:235], v[234:235], v[172:173], v[178:179] op_sel_hi:[1,0,1]
.Lgx0_sk6:
	s_lshr_b32 s98, s98, 1
	s_nop 1
	global_load_dwordx4 v[100:103], v220, s[38:39] offset:16
	global_load_dwordx4 v[96:99], v220, s[38:39]
	global_load_dwordx4 v[108:111], v220, s[40:41] offset:16
	global_load_dwordx4 v[104:107], v220, s[40:41]
	s_waitcnt vmcnt(28)
	s_add_i32 s21, s99, 7
	v_readlane_b32 s42, v222, s21
	v_readlane_b32 s43, v223, s21
	v_readlane_b32 s100, v224, s21
	v_readlane_b32 s101, v225, s21
	s_bitcmp1_b32 s98, 0
	s_cbranch_scc0 .Lgx0_sk7
	v_mul_f32_e32 v164, v112, v156
	v_mul_f32_e32 v165, v115, v157
	v_mul_f32_e32 v166, v117, v162
	v_mul_f32_e32 v167, v119, v163
	v_fmac_f32_e32 v164, v113, v158
	v_fmac_f32_e32 v165, v114, v159
	v_fmac_f32_e32 v166, v116, v160
	v_fmac_f32_e32 v167, v118, v161
	v_add_f32_e32 v164, v164, v165
	v_add_f32_e32 v164, v164, v166
	v_add_f32_e32 v164, v167, v164
	v_max_f32_e32 v168, v177, v177
	s_nop 0
	v_add_f32_dpp v164, v164, v164 quad_perm:[1,0,3,2] row_mask:0xf bank_mask:0xf bound_ctrl:1
	s_nop 1
	v_add_f32_dpp v164, v164, v164 quad_perm:[2,3,0,1] row_mask:0xf bank_mask:0xf bound_ctrl:1
	s_nop 1
	v_add_f32_dpp v164, v164, v164 row_half_mirror row_mask:0xf bank_mask:0xf bound_ctrl:1
	v_max_f32_e32 v168, v168, v164
	v_sub_f32_e32 v164, v164, v168
	v_sub_f32_e32 v172, v177, v168
	v_exp_f32_e32 v170, v164
	v_exp_f32_e32 v172, v172
	v_mov_b32_e32 v177, v168
	v_pk_mul_f32 v[174:175], v[120:121], v[170:171] op_sel_hi:[1,0]
	v_pk_mul_f32 v[178:179], v[124:125], v[170:171] op_sel_hi:[1,0]
	v_fma_f32 v176, v176, v172, v170
	v_pk_fma_f32 v[228:229], v[228:229], v[172:173], v[174:175] op_sel_hi:[1,0,1]
	v_pk_mul_f32 v[174:175], v[122:123], v[170:171] op_sel_hi:[1,0]
	v_pk_fma_f32 v[232:233], v[232:233], v[172:173], v[178:179] op_sel_hi:[1,0,1]
	v_pk_mul_f32 v[178:179], v[126:127], v[170:171] op_sel_hi:[1,0]
	v_pk_fma_f32 v[230:231], v[230:231], v[172:173], v[174:175] op_sel_hi:[1,0,1]
	v_pk_fma_f32 v[234:235], v[234:235], v[172:173], v[178:179] op_sel_hi:[1,0,1]
.Lgx0_sk7:
	s_lshr_b32 s98, s98, 1
	s_nop 1
	global_load_dwordx4 v[116:119], v220, s[42:43] offset:16
	global_load_dwordx4 v[112:115], v220, s[42:43]
	global_load_dwordx4 v[124:127], v220, s[100:101] offset:16
	global_load_dwordx4 v[120:123], v220, s[100:101]
	s_add_i32 s99, s99, 8
	s_cmp_lt_u32 s99, 32
	s_cbranch_scc1 .Lgx0_loop
	s_waitcnt vmcnt(28)
	s_bitcmp1_b32 s98, 0
	s_cbranch_scc0 .Lgx0_fk0
	v_mul_f32_e32 v164, v0, v156
	v_mul_f32_e32 v165, v3, v157
	v_mul_f32_e32 v166, v5, v162
	v_mul_f32_e32 v167, v7, v163
	v_fmac_f32_e32 v164, v1, v158
	v_fmac_f32_e32 v165, v2, v159
	v_fmac_f32_e32 v166, v4, v160
	v_fmac_f32_e32 v167, v6, v161
	v_add_f32_e32 v164, v164, v165
	v_add_f32_e32 v164, v164, v166
	v_add_f32_e32 v164, v167, v164
	v_max_f32_e32 v168, v177, v177
	s_nop 0
	v_add_f32_dpp v164, v164, v164 quad_perm:[1,0,3,2] row_mask:0xf bank_mask:0xf bound_ctrl:1
	s_nop 1
	v_add_f32_dpp v164, v164, v164 quad_perm:[2,3,0,1] row_mask:0xf bank_mask:0xf bound_ctrl:1
	s_nop 1
	v_add_f32_dpp v164, v164, v164 row_half_mirror row_mask:0xf bank_mask:0xf bound_ctrl:1
	v_max_f32_e32 v168, v168, v164
	v_sub_f32_e32 v164, v164, v168
	v_sub_f32_e32 v172, v177, v168
	v_exp_f32_e32 v170, v164
	v_exp_f32_e32 v172, v172
	v_mov_b32_e32 v177, v168
	v_pk_mul_f32 v[174:175], v[8:9], v[170:171] op_sel_hi:[1,0]
	v_pk_mul_f32 v[178:179], v[12:13], v[170:171] op_sel_hi:[1,0]
	v_fma_f32 v176, v176, v172, v170
	v_pk_fma_f32 v[228:229], v[228:229], v[172:173], v[174:175] op_sel_hi:[1,0,1]
	v_pk_mul_f32 v[174:175], v[10:11], v[170:171] op_sel_hi:[1,0]
	v_pk_fma_f32 v[232:233], v[232:233], v[172:173], v[178:179] op_sel_hi:[1,0,1]
	v_pk_mul_f32 v[178:179], v[14:15], v[170:171] op_sel_hi:[1,0]
	v_pk_fma_f32 v[230:231], v[230:231], v[172:173], v[174:175] op_sel_hi:[1,0,1]
	v_pk_fma_f32 v[234:235], v[234:235], v[172:173], v[178:179] op_sel_hi:[1,0,1]
.Lgx0_fk0:
	s_lshr_b32 s98, s98, 1
	s_waitcnt vmcnt(24)
	s_bitcmp1_b32 s98, 0
	s_cbranch_scc0 .Lgx0_fk1
	v_mul_f32_e32 v164, v16, v156
	v_mul_f32_e32 v165, v19, v157
	v_mul_f32_e32 v166, v21, v162
	v_mul_f32_e32 v167, v23, v163
	v_fmac_f32_e32 v164, v17, v158
	v_fmac_f32_e32 v165, v18, v159
	v_fmac_f32_e32 v166, v20, v160
	v_fmac_f32_e32 v167, v22, v161
	v_add_f32_e32 v164, v164, v165
	v_add_f32_e32 v164, v164, v166
	v_add_f32_e32 v164, v167, v164
	v_max_f32_e32 v168, v177, v177
	s_nop 0
	v_add_f32_dpp v164, v164, v164 quad_perm:[1,0,3,2] row_mask:0xf bank_mask:0xf bound_ctrl:1
	s_nop 1
	v_add_f32_dpp v164, v164, v164 quad_perm:[2,3,0,1] row_mask:0xf bank_mask:0xf bound_ctrl:1
	s_nop 1
	v_add_f32_dpp v164, v164, v164 row_half_mirror row_mask:0xf bank_mask:0xf bound_ctrl:1
	v_max_f32_e32 v168, v168, v164
	v_sub_f32_e32 v164, v164, v168
	v_sub_f32_e32 v172, v177, v168
	v_exp_f32_e32 v170, v164
	v_exp_f32_e32 v172, v172
	v_mov_b32_e32 v177, v168
	v_pk_mul_f32 v[174:175], v[24:25], v[170:171] op_sel_hi:[1,0]
	v_pk_mul_f32 v[178:179], v[28:29], v[170:171] op_sel_hi:[1,0]
	v_fma_f32 v176, v176, v172, v170
	v_pk_fma_f32 v[228:229], v[228:229], v[172:173], v[174:175] op_sel_hi:[1,0,1]
	v_pk_mul_f32 v[174:175], v[26:27], v[170:171] op_sel_hi:[1,0]
	v_pk_fma_f32 v[232:233], v[232:233], v[172:173], v[178:179] op_sel_hi:[1,0,1]
	v_pk_mul_f32 v[178:179], v[30:31], v[170:171] op_sel_hi:[1,0]
	v_pk_fma_f32 v[230:231], v[230:231], v[172:173], v[174:175] op_sel_hi:[1,0,1]
	v_pk_fma_f32 v[234:235], v[234:235], v[172:173], v[178:179] op_sel_hi:[1,0,1]
.Lgx0_fk1:
	s_lshr_b32 s98, s98, 1
	s_waitcnt vmcnt(20)
	s_bitcmp1_b32 s98, 0
	s_cbranch_scc0 .Lgx0_fk2
	v_mul_f32_e32 v164, v32, v156
	v_mul_f32_e32 v165, v35, v157
	v_mul_f32_e32 v166, v37, v162
	v_mul_f32_e32 v167, v39, v163
	v_fmac_f32_e32 v164, v33, v158
	v_fmac_f32_e32 v165, v34, v159
	v_fmac_f32_e32 v166, v36, v160
	v_fmac_f32_e32 v167, v38, v161
	v_add_f32_e32 v164, v164, v165
	v_add_f32_e32 v164, v164, v166
	v_add_f32_e32 v164, v167, v164
	v_max_f32_e32 v168, v177, v177
	s_nop 0
	v_add_f32_dpp v164, v164, v164 quad_perm:[1,0,3,2] row_mask:0xf bank_mask:0xf bound_ctrl:1
	s_nop 1
	v_add_f32_dpp v164, v164, v164 quad_perm:[2,3,0,1] row_mask:0xf bank_mask:0xf bound_ctrl:1
	s_nop 1
	v_add_f32_dpp v164, v164, v164 row_half_mirror row_mask:0xf bank_mask:0xf bound_ctrl:1
	v_max_f32_e32 v168, v168, v164
	v_sub_f32_e32 v164, v164, v168
	v_sub_f32_e32 v172, v177, v168
	v_exp_f32_e32 v170, v164
	v_exp_f32_e32 v172, v172
	v_mov_b32_e32 v177, v168
	v_pk_mul_f32 v[174:175], v[40:41], v[170:171] op_sel_hi:[1,0]
	v_pk_mul_f32 v[178:179], v[44:45], v[170:171] op_sel_hi:[1,0]
	v_fma_f32 v176, v176, v172, v170
	v_pk_fma_f32 v[228:229], v[228:229], v[172:173], v[174:175] op_sel_hi:[1,0,1]
	v_pk_mul_f32 v[174:175], v[42:43], v[170:171] op_sel_hi:[1,0]
	v_pk_fma_f32 v[232:233], v[232:233], v[172:173], v[178:179] op_sel_hi:[1,0,1]
	v_pk_mul_f32 v[178:179], v[46:47], v[170:171] op_sel_hi:[1,0]
	v_pk_fma_f32 v[230:231], v[230:231], v[172:173], v[174:175] op_sel_hi:[1,0,1]
	v_pk_fma_f32 v[234:235], v[234:235], v[172:173], v[178:179] op_sel_hi:[1,0,1]
.Lgx0_fk2:
	s_lshr_b32 s98, s98, 1
	s_waitcnt vmcnt(16)
	s_bitcmp1_b32 s98, 0
	s_cbranch_scc0 .Lgx0_fk3
	v_mul_f32_e32 v164, v48, v156
	v_mul_f32_e32 v165, v51, v157
	v_mul_f32_e32 v166, v53, v162
	v_mul_f32_e32 v167, v55, v163
	v_fmac_f32_e32 v164, v49, v158
	v_fmac_f32_e32 v165, v50, v159
	v_fmac_f32_e32 v166, v52, v160
	v_fmac_f32_e32 v167, v54, v161
	v_add_f32_e32 v164, v164, v165
	v_add_f32_e32 v164, v164, v166
	v_add_f32_e32 v164, v167, v164
	v_max_f32_e32 v168, v177, v177
	s_nop 0
	v_add_f32_dpp v164, v164, v164 quad_perm:[1,0,3,2] row_mask:0xf bank_mask:0xf bound_ctrl:1
	s_nop 1
	v_add_f32_dpp v164, v164, v164 quad_perm:[2,3,0,1] row_mask:0xf bank_mask:0xf bound_ctrl:1
	s_nop 1
	v_add_f32_dpp v164, v164, v164 row_half_mirror row_mask:0xf bank_mask:0xf bound_ctrl:1
	v_max_f32_e32 v168, v168, v164
	v_sub_f32_e32 v164, v164, v168
	v_sub_f32_e32 v172, v177, v168
	v_exp_f32_e32 v170, v164
	v_exp_f32_e32 v172, v172
	v_mov_b32_e32 v177, v168
	v_pk_mul_f32 v[174:175], v[56:57], v[170:171] op_sel_hi:[1,0]
	v_pk_mul_f32 v[178:179], v[60:61], v[170:171] op_sel_hi:[1,0]
	v_fma_f32 v176, v176, v172, v170
	v_pk_fma_f32 v[228:229], v[228:229], v[172:173], v[174:175] op_sel_hi:[1,0,1]
	v_pk_mul_f32 v[174:175], v[58:59], v[170:171] op_sel_hi:[1,0]
	v_pk_fma_f32 v[232:233], v[232:233], v[172:173], v[178:179] op_sel_hi:[1,0,1]
	v_pk_mul_f32 v[178:179], v[62:63], v[170:171] op_sel_hi:[1,0]
	v_pk_fma_f32 v[230:231], v[230:231], v[172:173], v[174:175] op_sel_hi:[1,0,1]
	v_pk_fma_f32 v[234:235], v[234:235], v[172:173], v[178:179] op_sel_hi:[1,0,1]
.Lgx0_fk3:
	s_lshr_b32 s98, s98, 1
	s_waitcnt vmcnt(12)
	s_bitcmp1_b32 s98, 0
	s_cbranch_scc0 .Lgx0_fk4
	v_mul_f32_e32 v164, v64, v156
	v_mul_f32_e32 v165, v67, v157
	v_mul_f32_e32 v166, v69, v162
	v_mul_f32_e32 v167, v71, v163
	v_fmac_f32_e32 v164, v65, v158
	v_fmac_f32_e32 v165, v66, v159
	v_fmac_f32_e32 v166, v68, v160
	v_fmac_f32_e32 v167, v70, v161
	v_add_f32_e32 v164, v164, v165
	v_add_f32_e32 v164, v164, v166
	v_add_f32_e32 v164, v167, v164
	v_max_f32_e32 v168, v177, v177
	s_nop 0
	v_add_f32_dpp v164, v164, v164 quad_perm:[1,0,3,2] row_mask:0xf bank_mask:0xf bound_ctrl:1
	s_nop 1
	v_add_f32_dpp v164, v164, v164 quad_perm:[2,3,0,1] row_mask:0xf bank_mask:0xf bound_ctrl:1
	s_nop 1
	v_add_f32_dpp v164, v164, v164 row_half_mirror row_mask:0xf bank_mask:0xf bound_ctrl:1
	v_max_f32_e32 v168, v168, v164
	v_sub_f32_e32 v164, v164, v168
	v_sub_f32_e32 v172, v177, v168
	v_exp_f32_e32 v170, v164
	v_exp_f32_e32 v172, v172
	v_mov_b32_e32 v177, v168
	v_pk_mul_f32 v[174:175], v[72:73], v[170:171] op_sel_hi:[1,0]
	v_pk_mul_f32 v[178:179], v[76:77], v[170:171] op_sel_hi:[1,0]
	v_fma_f32 v176, v176, v172, v170
	v_pk_fma_f32 v[228:229], v[228:229], v[172:173], v[174:175] op_sel_hi:[1,0,1]
	v_pk_mul_f32 v[174:175], v[74:75], v[170:171] op_sel_hi:[1,0]
	v_pk_fma_f32 v[232:233], v[232:233], v[172:173], v[178:179] op_sel_hi:[1,0,1]
	v_pk_mul_f32 v[178:179], v[78:79], v[170:171] op_sel_hi:[1,0]
	v_pk_fma_f32 v[230:231], v[230:231], v[172:173], v[174:175] op_sel_hi:[1,0,1]
	v_pk_fma_f32 v[234:235], v[234:235], v[172:173], v[178:179] op_sel_hi:[1,0,1]
.Lgx0_fk4:
	s_lshr_b32 s98, s98, 1
	s_waitcnt vmcnt(8)
	s_bitcmp1_b32 s98, 0
	s_cbranch_scc0 .Lgx0_fk5
	v_mul_f32_e32 v164, v80, v156
	v_mul_f32_e32 v165, v83, v157
	v_mul_f32_e32 v166, v85, v162
	v_mul_f32_e32 v167, v87, v163
	v_fmac_f32_e32 v164, v81, v158
	v_fmac_f32_e32 v165, v82, v159
	v_fmac_f32_e32 v166, v84, v160
	v_fmac_f32_e32 v167, v86, v161
	v_add_f32_e32 v164, v164, v165
	v_add_f32_e32 v164, v164, v166
	v_add_f32_e32 v164, v167, v164
	v_max_f32_e32 v168, v177, v177
	s_nop 0
	v_add_f32_dpp v164, v164, v164 quad_perm:[1,0,3,2] row_mask:0xf bank_mask:0xf bound_ctrl:1
	s_nop 1
	v_add_f32_dpp v164, v164, v164 quad_perm:[2,3,0,1] row_mask:0xf bank_mask:0xf bound_ctrl:1
	s_nop 1
	v_add_f32_dpp v164, v164, v164 row_half_mirror row_mask:0xf bank_mask:0xf bound_ctrl:1
	v_max_f32_e32 v168, v168, v164
	v_sub_f32_e32 v164, v164, v168
	v_sub_f32_e32 v172, v177, v168
	v_exp_f32_e32 v170, v164
	v_exp_f32_e32 v172, v172
	v_mov_b32_e32 v177, v168
	v_pk_mul_f32 v[174:175], v[88:89], v[170:171] op_sel_hi:[1,0]
	v_pk_mul_f32 v[178:179], v[92:93], v[170:171] op_sel_hi:[1,0]
	v_fma_f32 v176, v176, v172, v170
	v_pk_fma_f32 v[228:229], v[228:229], v[172:173], v[174:175] op_sel_hi:[1,0,1]
	v_pk_mul_f32 v[174:175], v[90:91], v[170:171] op_sel_hi:[1,0]
	v_pk_fma_f32 v[232:233], v[232:233], v[172:173], v[178:179] op_sel_hi:[1,0,1]
	v_pk_mul_f32 v[178:179], v[94:95], v[170:171] op_sel_hi:[1,0]
	v_pk_fma_f32 v[230:231], v[230:231], v[172:173], v[174:175] op_sel_hi:[1,0,1]
	v_pk_fma_f32 v[234:235], v[234:235], v[172:173], v[178:179] op_sel_hi:[1,0,1]
.Lgx0_fk5:
	s_lshr_b32 s98, s98, 1
	s_waitcnt vmcnt(4)
	s_bitcmp1_b32 s98, 0
	s_cbranch_scc0 .Lgx0_fk6
	v_mul_f32_e32 v164, v96, v156
	v_mul_f32_e32 v165, v99, v157
	v_mul_f32_e32 v166, v101, v162
	v_mul_f32_e32 v167, v103, v163
	v_fmac_f32_e32 v164, v97, v158
	v_fmac_f32_e32 v165, v98, v159
	v_fmac_f32_e32 v166, v100, v160
	v_fmac_f32_e32 v167, v102, v161
	v_add_f32_e32 v164, v164, v165
	v_add_f32_e32 v164, v164, v166
	v_add_f32_e32 v164, v167, v164
	v_max_f32_e32 v168, v177, v177
	s_nop 0
	v_add_f32_dpp v164, v164, v164 quad_perm:[1,0,3,2] row_mask:0xf bank_mask:0xf bound_ctrl:1
	s_nop 1
	v_add_f32_dpp v164, v164, v164 quad_perm:[2,3,0,1] row_mask:0xf bank_mask:0xf bound_ctrl:1
	s_nop 1
	v_add_f32_dpp v164, v164, v164 row_half_mirror row_mask:0xf bank_mask:0xf bound_ctrl:1
	v_max_f32_e32 v168, v168, v164
	v_sub_f32_e32 v164, v164, v168
	v_sub_f32_e32 v172, v177, v168
	v_exp_f32_e32 v170, v164
	v_exp_f32_e32 v172, v172
	v_mov_b32_e32 v177, v168
	v_pk_mul_f32 v[174:175], v[104:105], v[170:171] op_sel_hi:[1,0]
	v_pk_mul_f32 v[178:179], v[108:109], v[170:171] op_sel_hi:[1,0]
	v_fma_f32 v176, v176, v172, v170
	v_pk_fma_f32 v[228:229], v[228:229], v[172:173], v[174:175] op_sel_hi:[1,0,1]
	v_pk_mul_f32 v[174:175], v[106:107], v[170:171] op_sel_hi:[1,0]
	v_pk_fma_f32 v[232:233], v[232:233], v[172:173], v[178:179] op_sel_hi:[1,0,1]
	v_pk_mul_f32 v[178:179], v[110:111], v[170:171] op_sel_hi:[1,0]
	v_pk_fma_f32 v[230:231], v[230:231], v[172:173], v[174:175] op_sel_hi:[1,0,1]
	v_pk_fma_f32 v[234:235], v[234:235], v[172:173], v[178:179] op_sel_hi:[1,0,1]
.Lgx0_fk6:
	s_lshr_b32 s98, s98, 1
	s_waitcnt vmcnt(0)
	s_bitcmp1_b32 s98, 0
	s_cbranch_scc0 .Lgx0_fk7
	v_mul_f32_e32 v164, v112, v156
	v_mul_f32_e32 v165, v115, v157
	v_mul_f32_e32 v166, v117, v162
	v_mul_f32_e32 v167, v119, v163
	v_fmac_f32_e32 v164, v113, v158
	v_fmac_f32_e32 v165, v114, v159
	v_fmac_f32_e32 v166, v116, v160
	v_fmac_f32_e32 v167, v118, v161
	v_add_f32_e32 v164, v164, v165
	v_add_f32_e32 v164, v164, v166
	v_add_f32_e32 v164, v167, v164
	v_max_f32_e32 v168, v177, v177
	s_nop 0
	v_add_f32_dpp v164, v164, v164 quad_perm:[1,0,3,2] row_mask:0xf bank_mask:0xf bound_ctrl:1
	s_nop 1
	v_add_f32_dpp v164, v164, v164 quad_perm:[2,3,0,1] row_mask:0xf bank_mask:0xf bound_ctrl:1
	s_nop 1
	v_add_f32_dpp v164, v164, v164 row_half_mirror row_mask:0xf bank_mask:0xf bound_ctrl:1
	v_max_f32_e32 v168, v168, v164
	v_sub_f32_e32 v164, v164, v168
	v_sub_f32_e32 v172, v177, v168
	v_exp_f32_e32 v170, v164
	v_exp_f32_e32 v172, v172
	v_mov_b32_e32 v177, v168
	v_pk_mul_f32 v[174:175], v[120:121], v[170:171] op_sel_hi:[1,0]
	v_pk_mul_f32 v[178:179], v[124:125], v[170:171] op_sel_hi:[1,0]
	v_fma_f32 v176, v176, v172, v170
	v_pk_fma_f32 v[228:229], v[228:229], v[172:173], v[174:175] op_sel_hi:[1,0,1]
	v_pk_mul_f32 v[174:175], v[122:123], v[170:171] op_sel_hi:[1,0]
	v_pk_fma_f32 v[232:233], v[232:233], v[172:173], v[178:179] op_sel_hi:[1,0,1]
	v_pk_mul_f32 v[178:179], v[126:127], v[170:171] op_sel_hi:[1,0]
	v_pk_fma_f32 v[230:231], v[230:231], v[172:173], v[174:175] op_sel_hi:[1,0,1]
	v_pk_fma_f32 v[234:235], v[234:235], v[172:173], v[178:179] op_sel_hi:[1,0,1]
.Lgx0_fk7:
	s_lshr_b32 s98, s98, 1
	v_mov_b32_e32 v12, v228
	v_mov_b32_e32 v13, v229
	v_mov_b32_e32 v14, v230
	v_mov_b32_e32 v15, v231
	v_mov_b32_e32 v4, v232
	v_mov_b32_e32 v5, v233
	v_mov_b32_e32 v6, v234
	v_mov_b32_e32 v7, v235
	v_mov_b32_e32 v72, v176
	v_mov_b32_e32 v73, v177
	s_and_saveexec_b64 s[20:21], s[18:19]
	s_cbranch_execz .LBB0_2331
	v_lshl_add_u32 v0, s55, 6, v212
	v_add_u32_e32 v2, 0x8000, v0
	v_pk_mov_b32 v[0:1], v[72:73], v[72:73] op_sel:[1,0]
	ds_write2_b32 v2, v0, v1 offset1:1
	s_branch .LBB0_2331

.LBB0_2818:
	s_or_b64 exec, exec, s[20:21]
	s_mov_b32 s23, s31
	v_lshl_add_u64 v[0:1], v[150:151], 0, s[22:23]
	global_load_dwordx4 v[4:7], v[0:1], off
	s_lshl_b32 s20, s59, 8
	s_add_i32 s20, s20, 0
	v_mov_b32_e32 v0, s20
	s_waitcnt lgkmcnt(0)
	s_barrier
	v_lshlrev_b32_e32 v220, 2, v148
	v_mov_b32_e32 v139, v138
	v_mbcnt_lo_u32_b32 v236, -1, 0
	v_mbcnt_hi_u32_b32 v236, -1, v236
	v_and_b32_e32 v236, 31, v236
	v_lshl_add_u32 v236, v236, 3, s20
	ds_read_b64 v[222:223], v236 offset:28672
	ds_read_b64 v[224:225], v236 offset:30720
	s_lshl_b32 s23, s60, 9
	v_mov_b32_e32 v226, s24
	v_mov_b32_e32 v227, s25
	s_waitcnt vmcnt(0)
	v_lshlrev_b32_e32 v156, 16, v4
	v_and_b32_e32 v157, 0xffff0000, v5
	v_and_b32_e32 v158, 0xffff0000, v4
	v_lshlrev_b32_e32 v159, 16, v5
	v_lshlrev_b32_e32 v161, 16, v7
	v_lshlrev_b32_e32 v160, 16, v6
	v_and_b32_e32 v163, 0xffff0000, v7
	v_and_b32_e32 v162, 0xffff0000, v6
	v_mov_b32_e32 v177, 0xff800000
	v_mov_b32_e32 v176, 0
	v_mov_b32_e32 v228, 0
	v_mov_b32_e32 v229, 0
	v_mov_b32_e32 v230, 0
	v_mov_b32_e32 v231, 0
	v_mov_b32_e32 v232, 0
	v_mov_b32_e32 v233, 0
	v_mov_b32_e32 v234, 0
	v_mov_b32_e32 v235, 0
	v_mov_b32_e32 v171, 0
	v_mov_b32_e32 v173, 0
	s_waitcnt lgkmcnt(0)
	v_cmp_ne_u64_e32 vcc, 0, v[222:223]
	s_nop 1
	s_mov_b32 s98, vcc_lo
	v_cndmask_b32_e32 v222, v226, v222, vcc
	v_cndmask_b32_e32 v223, v227, v223, vcc
	v_cndmask_b32_e32 v224, v226, v224, vcc
	v_cndmask_b32_e32 v225, v227, v225, vcc
	s_nop 0
	v_readlane_b32 s38, v222, 0
	v_readlane_b32 s39, v223, 0
	v_readlane_b32 s40, v224, 0
	v_readlane_b32 s41, v225, 0
	v_readlane_b32 s42, v222, 1
	v_readlane_b32 s43, v223, 1
	v_readlane_b32 s100, v224, 1
	v_readlane_b32 s101, v225, 1
	global_load_dwordx4 v[4:7], v220, s[38:39] offset:16
	global_load_dwordx4 v[0:3], v220, s[38:39]
	global_load_dwordx4 v[12:15], v220, s[40:41] offset:16
	global_load_dwordx4 v[8:11], v220, s[40:41]
	v_readlane_b32 s38, v222, 2
	v_readlane_b32 s39, v223, 2
	v_readlane_b32 s40, v224, 2
	v_readlane_b32 s41, v225, 2
	global_load_dwordx4 v[20:23], v220, s[42:43] offset:16
	global_load_dwordx4 v[16:19], v220, s[42:43]
	global_load_dwordx4 v[28:31], v220, s[100:101] offset:16
	global_load_dwordx4 v[24:27], v220, s[100:101]
	v_readlane_b32 s42, v222, 3
	v_readlane_b32 s43, v223, 3
	v_readlane_b32 s100, v224, 3
	v_readlane_b32 s101, v225, 3
	global_load_dwordx4 v[36:39], v220, s[38:39] offset:16
	global_load_dwordx4 v[32:35], v220, s[38:39]
	global_load_dwordx4 v[44:47], v220, s[40:41] offset:16
	global_load_dwordx4 v[40:43], v220, s[40:41]
	v_readlane_b32 s38, v222, 4
	v_readlane_b32 s39, v223, 4
	v_readlane_b32 s40, v224, 4
	v_readlane_b32 s41, v225, 4
	global_load_dwordx4 v[52:55], v220, s[42:43] offset:16
	global_load_dwordx4 v[48:51], v220, s[42:43]
	global_load_dwordx4 v[60:63], v220, s[100:101] offset:16
	global_load_dwordx4 v[56:59], v220, s[100:101]
	v_readlane_b32 s42, v222, 5
	v_readlane_b32 s43, v223, 5
	v_readlane_b32 s100, v224, 5
	v_readlane_b32 s101, v225, 5
	global_load_dwordx4 v[68:71], v220, s[38:39] offset:16
	global_load_dwordx4 v[64:67], v220, s[38:39]
	global_load_dwordx4 v[76:79], v220, s[40:41] offset:16
	global_load_dwordx4 v[72:75], v220, s[40:41]
	v_readlane_b32 s38, v222, 6
	v_readlane_b32 s39, v223, 6
	v_readlane_b32 s40, v224, 6
	v_readlane_b32 s41, v225, 6
	global_load_dwordx4 v[84:87], v220, s[42:43] offset:16
	global_load_dwordx4 v[80:83], v220, s[42:43]
	global_load_dwordx4 v[92:95], v220, s[100:101] offset:16
	global_load_dwordx4 v[88:91], v220, s[100:101]
	v_readlane_b32 s42, v222, 7
	v_readlane_b32 s43, v223, 7
	v_readlane_b32 s100, v224, 7
	v_readlane_b32 s101, v225, 7
	global_load_dwordx4 v[100:103], v220, s[38:39] offset:16
	global_load_dwordx4 v[96:99], v220, s[38:39]
	global_load_dwordx4 v[108:111], v220, s[40:41] offset:16
	global_load_dwordx4 v[104:107], v220, s[40:41]
	s_nop 4
	global_load_dwordx4 v[116:119], v220, s[42:43] offset:16
	global_load_dwordx4 v[112:115], v220, s[42:43]
	global_load_dwordx4 v[124:127], v220, s[100:101] offset:16
	global_load_dwordx4 v[120:123], v220, s[100:101]
	s_mov_b32 s99, 8

.Lgx1_fk7:
	s_lshr_b32 s98, s98, 1
	v_mov_b32_e32 v12, v228
	v_mov_b32_e32 v13, v229
	v_mov_b32_e32 v14, v230
	v_mov_b32_e32 v15, v231
	v_mov_b32_e32 v4, v232
	v_mov_b32_e32 v5, v233
	v_mov_b32_e32 v6, v234
	v_mov_b32_e32 v7, v235
	v_mov_b32_e32 v72, v176
	v_mov_b32_e32 v73, v177
	s_and_saveexec_b64 s[20:21], s[18:19]
	s_cbranch_execz .LBB0_2702
	v_lshl_add_u32 v0, s59, 6, v212
	v_add_u32_e32 v2, 0x8000, v0
	v_pk_mov_b32 v[0:1], v[72:73], v[72:73] op_sel:[1,0]
	ds_write2_b32 v2, v0, v1 offset1:1
	s_branch .LBB0_2702
